# combo, phase-C balance k=3
# speedup vs baseline: 1.0052x; 1.0052x over previous
; __global__ void __launch_bounds__(256, 2) hybrid_megakernel(Params p) {
;     ...
;       int start = 0, mine = 0;
;       for (int g2 = 0; g2 <= gi; ++g2) {
;         const int n = 32 - g2;
;         const int d = (n <= 10) ? 2 : (n <= 22) ? 1 : 0;
;         if (g2 < gi) start += 2 * d; else mine = d;
;       }
;       start += ((vb >> 3) & 1) * mine;
.LBB0_407:
	s_cmp_ge_u32 s2, 3
	s_cselect_b64 s[4:5], -1, 0
	s_cmp_lt_u32 s2, 29
	v_cndmask_b32_e64 v1, 0, 1, s[4:5]
	s_cselect_b64 vcc, -1, 0
	v_cndmask_b32_e32 v1, 2, v1, vcc
	s_cmp_lt_i32 s2, s0
	v_lshlrev_b32_e32 v2, 1, v1
	s_cselect_b64 vcc, -1, 0
	s_add_i32 s2, s2, 1
	v_cndmask_b32_e32 v2, 0, v2, vcc
	v_cndmask_b32_e32 v116, v1, v116, vcc
	s_cmp_eq_u32 s1, s2
	v_add_u32_e32 v0, v2, v0
	s_cbranch_scc0 .LBB0_407
	v_cmp_gt_i32_e32 vcc, 1, v116
	s_cbranch_vccz .LBB0_410
	s_branch .LBB0_345
